# static younger-half priority in the attention pair loops combined with the s_sleep 8 stagger (flips still replaced by nops)
# speedup vs baseline: 1.0122x; 1.0004x over previous
; #define ATT_ISSUE2(p_, st_) do { LAS unsigned char* sp_ = lds + (st_) * STG2; const int ta_ = dual ? (p_) : 2 * (p_), tb_ = dual ? (p_) : 2 * (p_) + 1; ATT_ISSUE1(u, ta_, sp_); ATT_ISSUEM(ta_, sp_ + 2 * STAGEB); \
;         if (dual || tb_ < u.ntiles) { ATT_ISSUE1(ub, tb_, sp_ + STAGEB); ATT_ISSUEM(tb_, sp_ + 2 * STAGEB + MSKB); } } while (0)
;     ...
;         for (int p = p0; p < npairs; ++p) {
;             asm volatile("s_waitcnt vmcnt(0)" ::: "memory");
;             __builtin_amdgcn_s_barrier(); asm volatile("" ::: "memory");
;             if (p + 1 < npairs) ATT_ISSUE2(p + 1, (p + 1) & 1);
.LBB0_579:
	s_add_i32 s27, s2, 1
	s_waitcnt vmcnt(0)
	s_barrier
	v_readlane_b32 s98, v254, 11
	s_nop 3
	s_cmp_lt_u32 s98, 4
	s_cbranch_scc1 .Lstag_579
	s_sleep 8
	s_setprio 1

; #define ATT_ISSUE2(p_, st_) do { LAS unsigned char* sp_ = lds + (st_) * STG2; const int ta_ = dual ? (p_) : 2 * (p_), tb_ = dual ? (p_) : 2 * (p_) + 1; ATT_ISSUE1(u, ta_, sp_); ATT_ISSUEM(ta_, sp_ + 2 * STAGEB); \
;         if (dual || tb_ < u.ntiles) { ATT_ISSUE1(ub, tb_, sp_ + STAGEB); ATT_ISSUEM(tb_, sp_ + 2 * STAGEB + MSKB); } } while (0)
;     ...
;         for (int p = p0; p < npairs; ++p) {
;             asm volatile("s_waitcnt vmcnt(0)" ::: "memory");
;             __builtin_amdgcn_s_barrier(); asm volatile("" ::: "memory");
;             if (p + 1 < npairs) ATT_ISSUE2(p + 1, (p + 1) & 1);
.LBB0_2104:
	s_waitcnt vmcnt(0)
	s_barrier
	v_readlane_b32 s98, v254, 11
	s_nop 3
	s_cmp_lt_u32 s98, 4
	s_cbranch_scc1 .Lstag_2104
	s_sleep 8
	s_setprio 1

; #define ATT_ISSUE2(p_, st_) do { LAS unsigned char* sp_ = lds + (st_) * STG2; const int ta_ = dual ? (p_) : 2 * (p_), tb_ = dual ? (p_) : 2 * (p_) + 1; ATT_ISSUE1(u, ta_, sp_); ATT_ISSUEM(ta_, sp_ + 2 * STAGEB); \
;         if (dual || tb_ < u.ntiles) { ATT_ISSUE1(ub, tb_, sp_ + STAGEB); ATT_ISSUEM(tb_, sp_ + 2 * STAGEB + MSKB); } } while (0)
;     ...
;         for (int p = p0; p < npairs; ++p) {
;             asm volatile("s_waitcnt vmcnt(0)" ::: "memory");
;             __builtin_amdgcn_s_barrier(); asm volatile("" ::: "memory");
;             if (p + 1 < npairs) ATT_ISSUE2(p + 1, (p + 1) & 1);
.LBB0_3301:
	s_add_i32 s96, s97, 1
	s_waitcnt vmcnt(0)
	s_barrier
	v_readlane_b32 s98, v254, 11
	s_nop 3
	s_cmp_lt_u32 s98, 4
	s_cbranch_scc1 .Lstag_3301
	s_sleep 8
	s_setprio 1
